# P4 epilogue: counted waits per row group for the first x load batch (was one vmcnt(0)); zeroing with 64-bit moves
# speedup vs baseline: 1.0032x; 1.0032x over previous
; __device__ __forceinline__ unsigned cvt_pk_bf16(float lo, float hi) { const f32x2c_t v = {lo, hi}; const bf16x2c_t b = __builtin_convertvector(v, bf16x2c_t); return __builtin_bit_cast(unsigned, b); }
;     __device__ __forceinline__ void operator()(const f32x4 (&acc)[2][2][4][2], const Unit& u, int wr, int wc, int fr, int fq) const {
;     ...
;         for (int ai = 0; ai < 2; ++ai) {
;             f32x4 xv[4][2][2];
; #pragma unroll
;             for (int m = 0; m < 4; ++m)
; #pragma unroll
;                 for (int bj = 0; bj < 2; ++bj) { const size_t off = (size_t)(row0 + ai * HALF + m * 16) * DM + col0 + bj * HALF; xv[m][bj][0] = *(const f32x4*)(xbase + off); xv[m][bj][1] = *(const f32x4*)(xbase + off + 4); }
; #pragma unroll
;             for (int m = 0; m < 4; ++m) { const size_t r = (size_t)(row0 + ai * HALF + m * 16); float ss = 0.f;
; #pragma unroll
;                 for (int bj = 0; bj < 2; ++bj) { const size_t off = r * DM + col0 + bj * HALF;
;                     const f32x4 v0 = acc[ai][bj][m][0] * ascale + xv[m][bj][0], v1 = acc[ai][bj][m][1] * ascale + xv[m][bj][1];
;                     if (!WB) { *(f32x4*)(out + off) = v0; *(f32x4*)(out + off + 4) = v1; }
;                     if (WB) { u32x4 w; w.x = cvt_pk_bf16(v0[0], v0[1]); w.y = cvt_pk_bf16(v0[2], v0[3]); w.z = cvt_pk_bf16(v1[0], v1[1]); w.w = cvt_pk_bf16(v1[2], v1[3]); *(u32x4*)(xb + off) = w; }
;                     ss += (v0[0] * v0[0] + v0[1] * v0[1]) + (v0[2] * v0[2] + v0[3] * v0[3]) + (v1[0] * v1[0] + v1[1] * v1[1]) + (v1[2] * v1[2] + v1[3] * v1[3]); }
;                 ss += __shfl_xor(ss, 16); ss += __shfl_xor(ss, 32);
;                 if (fq == 0) ssq[r * 16 + u.pn * 4 + wc] = ss; }
;             asm volatile("" ::: "memory"); }
.LBB0_345:
	s_lshl_b32 s0, s52, 8
	v_and_b32_e32 v178, 63, v254
	s_add_i32 s0, s0, s64
	v_and_b32_e32 v205, 64, v204
	v_and_or_b32 v186, v178, 15, s0
	s_lshl_b32 s0, s50, 8
	s_or_b32 s0, s0, s65
	v_ashrrev_i32_e32 v128, 1, v178
	v_and_b32_e32 v128, -8, v128
	s_cmp_lt_i32 s52, 64
	v_add_u32_e32 v184, s0, v128
	s_cselect_b32 s0, s37, s62
	s_cselect_b32 s1, s36, s61
	v_mov_b32_e32 v128, s1
	v_mov_b32_e32 v129, s0
	v_ashrrev_i32_e32 v185, 31, v184
	v_ashrrev_i32_e32 v187, 31, v186
	v_lshl_add_u64 v[188:189], v[184:185], 2, v[128:129]
	v_lshlrev_b64 v[128:129], 12, v[186:187]
	v_lshl_add_u64 v[128:129], v[188:189], 0, v[128:129]
	global_load_dwordx4 v[180:183], v[128:129], off
	global_load_dwordx4 v[206:209], v[128:129], off offset:16
	global_load_dwordx4 v[210:213], v[128:129], off offset:512
	global_load_dwordx4 v[214:217], v[128:129], off offset:528
	v_or_b32_e32 v194, 16, v186
	v_or_b32_e32 v192, 32, v186
	v_or_b32_e32 v190, 48, v186
	v_ashrrev_i32_e32 v195, 31, v194
	v_ashrrev_i32_e32 v193, 31, v192
	v_ashrrev_i32_e32 v191, 31, v190
	v_lshlrev_b64 v[128:129], 12, v[194:195]
	v_lshlrev_b64 v[130:131], 12, v[192:193]
	v_lshlrev_b64 v[132:133], 12, v[190:191]
	v_lshl_add_u64 v[128:129], v[188:189], 0, v[128:129]
	v_lshl_add_u64 v[130:131], v[188:189], 0, v[130:131]
	v_lshl_add_u64 v[132:133], v[188:189], 0, v[132:133]
	global_load_dwordx4 v[168:171], v[128:129], off offset:16
	global_load_dwordx4 v[172:175], v[128:129], off
	global_load_dwordx4 v[160:163], v[128:129], off offset:528
	global_load_dwordx4 v[164:167], v[128:129], off offset:512
	global_load_dwordx4 v[152:155], v[130:131], off offset:16
	global_load_dwordx4 v[156:159], v[130:131], off
	global_load_dwordx4 v[144:147], v[130:131], off offset:528
	global_load_dwordx4 v[148:151], v[130:131], off offset:512
	global_load_dwordx4 v[136:139], v[132:133], off offset:16
	global_load_dwordx4 v[140:143], v[132:133], off
	s_nop 0
	global_load_dwordx4 v[128:131], v[132:133], off offset:528
	s_nop 0
	global_load_dwordx4 v[132:135], v[132:133], off offset:512
	v_xor_b32_e32 v196, 16, v204
	v_add_u32_e32 v205, 64, v205
	v_cmp_lt_i32_e32 vcc, v196, v205
	v_xor_b32_e32 v218, 32, v204
	s_lshl_b32 s10, s50, 2
	v_cndmask_b32_e32 v196, v204, v196, vcc
	v_cmp_lt_i32_e32 vcc, v218, v205
	v_lshlrev_b32_e32 v205, 2, v196
	s_ashr_i32 s11, s10, 31
	v_cndmask_b32_e32 v218, v204, v218, vcc
	v_cmp_gt_u32_e32 vcc, 16, v178
	v_lshlrev_b32_e32 v178, 2, v218
	v_lshlrev_b64 v[218:219], 11, v[186:187]
	s_waitcnt vmcnt(12)
	v_pk_fma_f32 v[118:119], v[118:119], s[40:41], v[182:183] op_sel_hi:[1,0,1]
	v_pk_fma_f32 v[116:117], v[116:117], s[40:41], v[180:181] op_sel_hi:[1,0,1]
	v_pk_fma_f32 v[126:127], v[126:127], s[40:41], v[212:213] op_sel_hi:[1,0,1]
	v_pk_fma_f32 v[124:125], v[124:125], s[40:41], v[210:211] op_sel_hi:[1,0,1]
	v_pk_fma_f32 v[182:183], v[112:113], s[40:41], v[206:207] op_sel_hi:[1,0,1]
	v_pk_fma_f32 v[120:121], v[120:121], s[40:41], v[214:215] op_sel_hi:[1,0,1]
	v_cvt_pk_bf16_f32 v112, v116, v117
	v_cvt_pk_bf16_f32 v113, v118, v119
	v_mul_f32_e32 v117, v117, v117
	v_mul_f32_e32 v119, v119, v119
	v_mul_f32_e32 v196, v125, v125
	v_mul_f32_e32 v206, v127, v127
	v_pk_fma_f32 v[180:181], v[114:115], s[40:41], v[208:209] op_sel_hi:[1,0,1]
	v_pk_fma_f32 v[122:123], v[122:123], s[40:41], v[216:217] op_sel_hi:[1,0,1]
	v_cvt_pk_bf16_f32 v114, v182, v183
	v_mul_f32_e32 v183, v183, v183
	v_mul_f32_e32 v207, v121, v121
	v_fmac_f32_e32 v117, v116, v116
	v_fmac_f32_e32 v119, v118, v118
	v_fmac_f32_e32 v196, v124, v124
	v_fmac_f32_e32 v206, v126, v126
	v_cvt_pk_bf16_f32 v115, v180, v181
	v_mul_f32_e32 v181, v181, v181
	v_mul_f32_e32 v208, v123, v123
	v_fmac_f32_e32 v183, v182, v182
	v_fmac_f32_e32 v207, v120, v120
	v_add_f32_e32 v116, v117, v119
	v_add_f32_e32 v117, v196, v206
	v_fmac_f32_e32 v181, v180, v180
	v_add_f32_e32 v116, v183, v116
	v_add_f32_e32 v117, v207, v117
	v_fmac_f32_e32 v208, v122, v122
	v_add_f32_e32 v116, v181, v116
	v_add_f32_e32 v117, v208, v117
	v_add_f32_e32 v180, v116, v117
	ds_bpermute_b32 v181, v205, v180
	v_lshl_add_u64 v[116:117], s[16:17], 0, v[218:219]
	v_lshl_add_u64 v[118:119], v[184:185], 1, v[116:117]
	global_store_dwordx4 v[118:119], v[112:115], off
	v_cvt_pk_bf16_f32 v116, v120, v121
	v_cvt_pk_bf16_f32 v117, v122, v123
	s_waitcnt lgkmcnt(0)
	v_add_f32_e32 v112, v180, v181
	ds_bpermute_b32 v113, v178, v112
	v_cvt_pk_bf16_f32 v114, v124, v125
	v_cvt_pk_bf16_f32 v115, v126, v127
	global_store_dwordx4 v[118:119], v[114:117], off offset:256
	s_and_saveexec_b64 s[50:51], vcc
	s_cbranch_execz .LBB0_347
	v_lshlrev_b64 v[114:115], 6, v[186:187]
	v_lshl_add_u64 v[114:115], s[12:13], 0, v[114:115]
	v_lshl_add_u64 v[114:115], s[10:11], 2, v[114:115]
	s_lshl_b32 s0, s63, 2
	s_mov_b32 s1, s8
	v_lshl_add_u64 v[114:115], v[114:115], 0, s[0:1]
	s_waitcnt lgkmcnt(0)
	v_add_f32_e32 v112, v112, v113
	global_store_dword v[114:115], v112, off
; __device__ __forceinline__ unsigned cvt_pk_bf16(float lo, float hi) { const f32x2c_t v = {lo, hi}; const bf16x2c_t b = __builtin_convertvector(v, bf16x2c_t); return __builtin_bit_cast(unsigned, b); }
;     __device__ __forceinline__ void operator()(const f32x4 (&acc)[2][2][4][2], const Unit& u, int wr, int wc, int fr, int fq) const {
;     ...
;             for (int m = 0; m < 4; ++m) { const size_t r = (size_t)(row0 + ai * HALF + m * 16); float ss = 0.f;
; #pragma unroll
;                 for (int bj = 0; bj < 2; ++bj) { const size_t off = r * DM + col0 + bj * HALF;
;                     const f32x4 v0 = acc[ai][bj][m][0] * ascale + xv[m][bj][0], v1 = acc[ai][bj][m][1] * ascale + xv[m][bj][1];
;                     if (!WB) { *(f32x4*)(out + off) = v0; *(f32x4*)(out + off + 4) = v1; }
;                     if (WB) { u32x4 w; w.x = cvt_pk_bf16(v0[0], v0[1]); w.y = cvt_pk_bf16(v0[2], v0[3]); w.z = cvt_pk_bf16(v1[0], v1[1]); w.w = cvt_pk_bf16(v1[2], v1[3]); *(u32x4*)(xb + off) = w; }
;                     ss += (v0[0] * v0[0] + v0[1] * v0[1]) + (v0[2] * v0[2] + v0[3] * v0[3]) + (v1[0] * v1[0] + v1[1] * v1[1]) + (v1[2] * v1[2] + v1[3] * v1[3]); }
;                 ss += __shfl_xor(ss, 16); ss += __shfl_xor(ss, 32);
;                 if (fq == 0) ssq[r * 16 + u.pn * 4 + wc] = ss; }
.LBB0_347:
	s_or_b64 exec, exec, s[50:51]
	s_waitcnt vmcnt(11)
	v_pk_fma_f32 v[108:109], v[108:109], s[40:41], v[172:173] op_sel_hi:[1,0,1]
	v_pk_fma_f32 v[110:111], v[110:111], s[40:41], v[174:175] op_sel_hi:[1,0,1]
	v_pk_fma_f32 v[116:117], v[100:101], s[40:41], v[168:169] op_sel_hi:[1,0,1]
	v_cvt_pk_bf16_f32 v100, v108, v109
	v_mul_f32_e32 v109, v109, v109
	v_fmac_f32_e32 v109, v108, v108
	v_mul_f32_e32 v108, v111, v111
	v_fmac_f32_e32 v108, v110, v110
	v_add_f32_e32 v108, v109, v108
	v_mul_f32_e32 v109, v117, v117
	v_pk_fma_f32 v[106:107], v[106:107], s[40:41], v[166:167] op_sel_hi:[1,0,1]
	v_pk_fma_f32 v[104:105], v[104:105], s[40:41], v[164:165] op_sel_hi:[1,0,1]
	v_pk_fma_f32 v[114:115], v[102:103], s[40:41], v[170:171] op_sel_hi:[1,0,1]
	v_cvt_pk_bf16_f32 v101, v110, v111
	v_fmac_f32_e32 v109, v116, v116
	v_pk_fma_f32 v[110:111], v[96:97], s[40:41], v[160:161] op_sel_hi:[1,0,1]
	v_mul_f32_e32 v96, v105, v105
	v_mul_f32_e32 v97, v107, v107
	v_add_f32_e32 v108, v109, v108
	v_mul_f32_e32 v109, v115, v115
	v_fmac_f32_e32 v96, v104, v104
	v_fmac_f32_e32 v97, v106, v106
	v_fmac_f32_e32 v109, v114, v114
	v_add_f32_e32 v96, v96, v97
	v_mul_f32_e32 v97, v111, v111
	v_cvt_pk_bf16_f32 v103, v114, v115
	v_add_f32_e32 v114, v109, v108
	v_pk_fma_f32 v[108:109], v[98:99], s[40:41], v[162:163] op_sel_hi:[1,0,1]
	v_fmac_f32_e32 v97, v110, v110
	v_add_f32_e32 v96, v97, v96
	v_mul_f32_e32 v97, v109, v109
	v_fmac_f32_e32 v97, v108, v108
	v_add_f32_e32 v96, v97, v96
	v_add_f32_e32 v99, v114, v96
	ds_bpermute_b32 v114, v205, v99
	s_waitcnt lgkmcnt(1)
	v_lshlrev_b64 v[112:113], 11, v[194:195]
	v_lshl_add_u64 v[96:97], s[16:17], 0, v[112:113]
	v_lshl_add_u64 v[112:113], v[184:185], 1, v[96:97]
	v_cvt_pk_bf16_f32 v102, v116, v117
	s_waitcnt lgkmcnt(0)
	v_add_f32_e32 v96, v99, v114
	ds_bpermute_b32 v97, v178, v96
	global_store_dwordx4 v[112:113], v[100:103], off
	v_cvt_pk_bf16_f32 v98, v104, v105
	v_cvt_pk_bf16_f32 v99, v106, v107
	v_cvt_pk_bf16_f32 v100, v110, v111
	v_cvt_pk_bf16_f32 v101, v108, v109
	global_store_dwordx4 v[112:113], v[98:101], off offset:256
	s_and_saveexec_b64 s[50:51], vcc
	s_cbranch_execz .LBB0_349
	v_lshlrev_b64 v[98:99], 6, v[194:195]
	v_lshl_add_u64 v[98:99], s[12:13], 0, v[98:99]
	v_lshl_add_u64 v[98:99], s[10:11], 2, v[98:99]
	s_lshl_b32 s0, s63, 2
	s_mov_b32 s1, s8
	v_lshl_add_u64 v[98:99], v[98:99], 0, s[0:1]
	s_waitcnt lgkmcnt(0)
	v_add_f32_e32 v96, v96, v97
	global_store_dword v[98:99], v96, off
; __device__ __forceinline__ unsigned cvt_pk_bf16(float lo, float hi) { const f32x2c_t v = {lo, hi}; const bf16x2c_t b = __builtin_convertvector(v, bf16x2c_t); return __builtin_bit_cast(unsigned, b); }
;     __device__ __forceinline__ void operator()(const f32x4 (&acc)[2][2][4][2], const Unit& u, int wr, int wc, int fr, int fq) const {
;     ...
;             for (int m = 0; m < 4; ++m) { const size_t r = (size_t)(row0 + ai * HALF + m * 16); float ss = 0.f;
; #pragma unroll
;                 for (int bj = 0; bj < 2; ++bj) { const size_t off = r * DM + col0 + bj * HALF;
;                     const f32x4 v0 = acc[ai][bj][m][0] * ascale + xv[m][bj][0], v1 = acc[ai][bj][m][1] * ascale + xv[m][bj][1];
;                     if (!WB) { *(f32x4*)(out + off) = v0; *(f32x4*)(out + off + 4) = v1; }
;                     if (WB) { u32x4 w; w.x = cvt_pk_bf16(v0[0], v0[1]); w.y = cvt_pk_bf16(v0[2], v0[3]); w.z = cvt_pk_bf16(v1[0], v1[1]); w.w = cvt_pk_bf16(v1[2], v1[3]); *(u32x4*)(xb + off) = w; }
;                     ss += (v0[0] * v0[0] + v0[1] * v0[1]) + (v0[2] * v0[2] + v0[3] * v0[3]) + (v1[0] * v1[0] + v1[1] * v1[1]) + (v1[2] * v1[2] + v1[3] * v1[3]); }
;                 ss += __shfl_xor(ss, 16); ss += __shfl_xor(ss, 32);
;                 if (fq == 0) ssq[r * 16 + u.pn * 4 + wc] = ss; }
;             asm volatile("" ::: "memory"); }
.LBB0_349:
	s_or_b64 exec, exec, s[50:51]
	s_waitcnt vmcnt(10)
	v_pk_fma_f32 v[92:93], v[92:93], s[40:41], v[156:157] op_sel_hi:[1,0,1]
	v_pk_fma_f32 v[94:95], v[94:95], s[40:41], v[158:159] op_sel_hi:[1,0,1]
	v_pk_fma_f32 v[100:101], v[84:85], s[40:41], v[152:153] op_sel_hi:[1,0,1]
	v_cvt_pk_bf16_f32 v84, v92, v93
	v_mul_f32_e32 v93, v93, v93
	v_fmac_f32_e32 v93, v92, v92
	v_mul_f32_e32 v92, v95, v95
	v_fmac_f32_e32 v92, v94, v94
	v_add_f32_e32 v92, v93, v92
	v_mul_f32_e32 v93, v101, v101
	v_pk_fma_f32 v[90:91], v[90:91], s[40:41], v[150:151] op_sel_hi:[1,0,1]
	v_pk_fma_f32 v[88:89], v[88:89], s[40:41], v[148:149] op_sel_hi:[1,0,1]
	v_pk_fma_f32 v[98:99], v[86:87], s[40:41], v[154:155] op_sel_hi:[1,0,1]
	v_cvt_pk_bf16_f32 v85, v94, v95
	v_fmac_f32_e32 v93, v100, v100
	v_pk_fma_f32 v[94:95], v[80:81], s[40:41], v[144:145] op_sel_hi:[1,0,1]
	v_mul_f32_e32 v80, v89, v89
	v_mul_f32_e32 v81, v91, v91
	v_add_f32_e32 v92, v93, v92
	v_mul_f32_e32 v93, v99, v99
	v_fmac_f32_e32 v80, v88, v88
	v_fmac_f32_e32 v81, v90, v90
	v_fmac_f32_e32 v93, v98, v98
	v_add_f32_e32 v80, v80, v81
	v_mul_f32_e32 v81, v95, v95
	v_cvt_pk_bf16_f32 v87, v98, v99
	v_add_f32_e32 v98, v93, v92
	v_pk_fma_f32 v[92:93], v[82:83], s[40:41], v[146:147] op_sel_hi:[1,0,1]
	v_fmac_f32_e32 v81, v94, v94
	v_add_f32_e32 v80, v81, v80
	v_mul_f32_e32 v81, v93, v93
	v_fmac_f32_e32 v81, v92, v92
	v_add_f32_e32 v80, v81, v80
	v_add_f32_e32 v83, v98, v80
	ds_bpermute_b32 v98, v205, v83
	s_waitcnt lgkmcnt(1)
	v_lshlrev_b64 v[96:97], 11, v[192:193]
	v_lshl_add_u64 v[80:81], s[16:17], 0, v[96:97]
	v_lshl_add_u64 v[96:97], v[184:185], 1, v[80:81]
	v_cvt_pk_bf16_f32 v86, v100, v101
	s_waitcnt lgkmcnt(0)
	v_add_f32_e32 v80, v83, v98
	ds_bpermute_b32 v81, v178, v80
	global_store_dwordx4 v[96:97], v[84:87], off
	v_cvt_pk_bf16_f32 v82, v88, v89
	v_cvt_pk_bf16_f32 v83, v90, v91
	v_cvt_pk_bf16_f32 v84, v94, v95
	v_cvt_pk_bf16_f32 v85, v92, v93
	global_store_dwordx4 v[96:97], v[82:85], off offset:256
	s_and_saveexec_b64 s[50:51], vcc
	s_cbranch_execz .LBB0_351
	v_lshlrev_b64 v[82:83], 6, v[192:193]
	v_lshl_add_u64 v[82:83], s[12:13], 0, v[82:83]
	v_lshl_add_u64 v[82:83], s[10:11], 2, v[82:83]
	s_lshl_b32 s0, s63, 2
	s_mov_b32 s1, s8
	v_lshl_add_u64 v[82:83], v[82:83], 0, s[0:1]
	s_waitcnt lgkmcnt(0)
	v_add_f32_e32 v80, v80, v81
	global_store_dword v[82:83], v80, off
.LBB0_351:
	s_or_b64 exec, exec, s[50:51]
	s_waitcnt vmcnt(9)
	v_pk_fma_f32 v[76:77], v[76:77], s[40:41], v[140:141] op_sel_hi:[1,0,1]
	v_pk_fma_f32 v[78:79], v[78:79], s[40:41], v[142:143] op_sel_hi:[1,0,1]
	v_pk_fma_f32 v[84:85], v[68:69], s[40:41], v[136:137] op_sel_hi:[1,0,1]
	v_cvt_pk_bf16_f32 v68, v76, v77
	v_mul_f32_e32 v77, v77, v77
	v_fmac_f32_e32 v77, v76, v76
	v_mul_f32_e32 v76, v79, v79
	v_fmac_f32_e32 v76, v78, v78
	v_add_f32_e32 v76, v77, v76
	v_mul_f32_e32 v77, v85, v85
	v_pk_fma_f32 v[74:75], v[74:75], s[40:41], v[134:135] op_sel_hi:[1,0,1]
	v_pk_fma_f32 v[72:73], v[72:73], s[40:41], v[132:133] op_sel_hi:[1,0,1]
	v_pk_fma_f32 v[82:83], v[70:71], s[40:41], v[138:139] op_sel_hi:[1,0,1]
	v_cvt_pk_bf16_f32 v69, v78, v79
	v_fmac_f32_e32 v77, v84, v84
	v_pk_fma_f32 v[78:79], v[64:65], s[40:41], v[128:129] op_sel_hi:[1,0,1]
	v_mul_f32_e32 v64, v73, v73
	v_mul_f32_e32 v65, v75, v75
	v_add_f32_e32 v76, v77, v76
	v_mul_f32_e32 v77, v83, v83
	v_fmac_f32_e32 v64, v72, v72
	v_fmac_f32_e32 v65, v74, v74
	v_fmac_f32_e32 v77, v82, v82
	v_add_f32_e32 v64, v64, v65
	v_mul_f32_e32 v65, v79, v79
	v_cvt_pk_bf16_f32 v71, v82, v83
	v_add_f32_e32 v82, v77, v76
	v_pk_fma_f32 v[76:77], v[66:67], s[40:41], v[130:131] op_sel_hi:[1,0,1]
	v_fmac_f32_e32 v65, v78, v78
	v_add_f32_e32 v64, v65, v64
	v_mul_f32_e32 v65, v77, v77
	v_fmac_f32_e32 v65, v76, v76
	v_add_f32_e32 v64, v65, v64
	v_add_f32_e32 v67, v82, v64
	ds_bpermute_b32 v82, v205, v67
	s_waitcnt lgkmcnt(1)
	v_lshlrev_b64 v[80:81], 11, v[190:191]
	v_lshl_add_u64 v[64:65], s[16:17], 0, v[80:81]
	v_lshl_add_u64 v[80:81], v[184:185], 1, v[64:65]
	v_cvt_pk_bf16_f32 v70, v84, v85
	s_waitcnt lgkmcnt(0)
	v_add_f32_e32 v64, v67, v82
	ds_bpermute_b32 v65, v178, v64
	global_store_dwordx4 v[80:81], v[68:71], off
	v_cvt_pk_bf16_f32 v66, v72, v73
	v_cvt_pk_bf16_f32 v67, v74, v75
	v_cvt_pk_bf16_f32 v68, v78, v79
	v_cvt_pk_bf16_f32 v69, v76, v77
	global_store_dwordx4 v[80:81], v[66:69], off offset:256
	s_and_saveexec_b64 s[50:51], vcc
	s_cbranch_execz .LBB0_353
	v_lshlrev_b64 v[66:67], 6, v[190:191]
	v_lshl_add_u64 v[66:67], s[12:13], 0, v[66:67]
	v_lshl_add_u64 v[66:67], s[10:11], 2, v[66:67]
	s_lshl_b32 s0, s63, 2
	s_mov_b32 s1, s8
	v_lshl_add_u64 v[66:67], v[66:67], 0, s[0:1]
	s_waitcnt lgkmcnt(0)
	v_add_f32_e32 v64, v64, v65
	global_store_dword v[66:67], v64, off
